# scan loop: no vmcnt(0) drain per chunk; tile loads waited with counted waits that leave the previous epilogue's y stores / z loads (or x rows) in flight; CB phase B-row lane remap
# speedup vs baseline: 1.0613x; 1.0295x over previous
; DI u32x4 pack8(const float (&f)[8]) { u32x4 r; r[0] = pk2(f[0], f[1]); r[1] = pk2(f[2], f[3]); r[2] = pk2(f[4], f[5]); r[3] = pk2(f[6], f[7]); return r; }
; DI void ssd_scan_phase(bf16_t* P, const bf16_t* BT, const bf16_t* Cc, const bf16_t* CB, const float* dt, const float* acs,
;                        const float* cw, const float* cb, const float* Dp, char* lds, bool dry, int mode, float* Sbuf) {
;     ...
;     __syncthreads();
; #pragma unroll 1
;     for (int c = c0; c < c1; ++c) {
;       const size_t t0 = tb + c * 128;
;       const float* cAcs = sAcs + (c & 1) * 128; const float* cDt = sDt + (c & 1) * 128;
;       {
;         int xl = xl_, xc = xc_, r0 = r0_, cch = cch_;
;         asm volatile("" : "+v"(xl), "+v"(xc), "+v"(r0), "+v"(cch));
;         const f32x4 a0 = *(const f32x4*)(cAcs + cch * 8), a1 = *(const f32x4*)(cAcs + cch * 8 + 4);
;         const float L2E = 1.44269504f;
;         const float as[8] = {a0[0] * L2E, a0[1] * L2E, a0[2] * L2E, a0[3] * L2E, a1[0] * L2E, a1[1] * L2E, a1[2] * L2E, a1[3] * L2E};
; #pragma unroll
;         for (int j = 0; j < 4; ++j) {
;           const int r = r0 + 32 * j;
;           *(u32x4*)(sBT + swz128(r, cch)) = rB[j];
;           if (mode == 0) {
;             *(u32x4*)(sC + swz128(r, cch)) = rC[j];
;             float f[8]; unpack8(rCB[j], f);
;             const float el = cAcs[r] * L2E;
;             const int lim = r - cch * 8;
; #pragma unroll
;             for (int e = 0; e < 8; ++e) f[e] = (e <= lim) ? f[e] * __builtin_amdgcn_exp2f(el - as[e]) : 0.f;
;             *(u32x4*)(sCBL + swz128(r, cch)) = pack8(f);
;           }
;         }
.LBB0_1053:
	s_or_b64 exec, exec, s[78:79]
	v_readlane_b32 s4, v253, 16
	s_add_i32 s69, s80, s28
	v_readlane_b32 s18, v253, 30
	v_readlane_b32 s19, v253, 31
	s_add_u32 s72, s18, s34
	v_readlane_b32 s16, v253, 28
	s_addc_u32 s73, s19, 0
	s_mov_b32 s75, s35
	v_lshl_add_u64 v[20:21], v[124:125], 0, s[76:77]
	s_lshl_b64 s[76:77], s[80:81], 17
	v_readlane_b32 s17, v253, 29
	v_lshl_add_u64 v[164:165], v[150:151], 0, s[74:75]
	v_lshl_add_u64 v[166:167], v[152:153], 0, s[74:75]
	s_add_u32 s74, s16, s76
	s_addc_u32 s75, s17, s77
	s_add_u32 s76, s20, s76
	s_addc_u32 s77, s21, s77
	s_lshl_b32 s78, s80, 13
	s_add_i32 s85, s78, 0x2000
	s_lshl_b32 s78, s80, 7
	s_waitcnt vmcnt(0)
	v_mov_b32_e32 v157, v156
	v_lshlrev_b64 v[168:169], 1, v[20:21]
	v_mov_b32_e32 v170, s78
	s_waitcnt lgkmcnt(0)
	s_barrier
	v_readlane_b32 s5, v253, 17
	v_readlane_b32 s6, v253, 18
	v_readlane_b32 s7, v253, 19
	v_readlane_b32 s8, v253, 20
	v_readlane_b32 s9, v253, 21
	v_readlane_b32 s10, v253, 22
	v_readlane_b32 s11, v253, 23
	v_readlane_b32 s12, v253, 24
	v_readlane_b32 s13, v253, 25
	v_readlane_b32 s14, v253, 26
	v_readlane_b32 s15, v253, 27
.LBB0_1054:
	s_and_b32 s90, s80, 1
	s_lshl_b32 s78, s90, 9
	s_add_i32 s88, s78, 0
	s_add_i32 s88, s88, 0x22800
	v_mov_b32_e32 v34, v177
	v_mov_b32_e32 v40, v178
	v_mov_b32_e32 v29, v176
	v_mov_b32_e32 v41, v179
	s_mov_b64 s[78:79], -1
	v_lshl_add_u32 v24, v34, 5, s88
	ds_read_b128 v[20:23], v24
	ds_read_b128 v[30:33], v24 offset:16
	v_lshl_add_u32 v47, v29, 2, s88
	ds_read_b32 v48, v47
	ds_read_b32 v49, v47 offset:128
	ds_read_b32 v50, v47 offset:256
	ds_read_b32 v51, v47 offset:384
	v_lshlrev_b32_e32 v26, 3, v34
	s_and_b64 vcc, exec, s[56:57]
	s_waitcnt lgkmcnt(5)
	v_mul_f32_e32 v24, 0x3fb8aa3b, v23
	s_waitcnt lgkmcnt(4)
	v_mul_f32_e32 v23, 0x3fb8aa3b, v30
	v_bitop3_b32 v30, v29, v34, 15 bitop3:0x6c
	v_mul_f32_e32 v27, 0x3fb8aa3b, v21
	v_mul_f32_e32 v21, 0x3fb8aa3b, v32
	v_lshlrev_b32_e32 v30, 4, v30
	v_lshlrev_b32_e32 v32, 8, v29
	v_mul_f32_e32 v25, 0x3fb8aa3b, v22
	v_mul_f32_e32 v22, 0x3fb8aa3b, v31
	v_add_u32_e32 v31, v30, v32
	v_mul_f32_e32 v28, 0x3fb8aa3b, v20
	v_mul_f32_e32 v20, 0x3fb8aa3b, v33
	v_add_u32_e32 v33, 0, v31
	v_add_u32_e32 v31, 0x10000, v33
	s_cmp_lg_u64 s[42:43], 0
	s_cbranch_scc1 .Lscan_w47_0
	s_waitcnt vmcnt(17)
	s_branch .Lscan_wdone_0
.Lscan_w47_0:
	s_waitcnt vmcnt(14)
.Lscan_wdone_0:
	ds_write_b128 v31, v[60:63]
	v_lshl_add_u32 v31, v29, 2, s88
	s_cbranch_vccnz .LBB0_1056
	ds_write_b128 v33, v[52:55] offset:32768
	v_lshlrev_b32_e32 v34, 16, v56
	v_sub_u32_e32 v46, v29, v26
	v_cmp_lt_i32_e32 vcc, -1, v46
	v_lshlrev_b32_e32 v42, 16, v58
	s_waitcnt lgkmcnt(0)
	v_fma_f32 v35, v48, s29, -v28
	v_fma_f32 v37, v48, s29, -v27
	v_exp_f32_e32 v36, v35
	v_exp_f32_e32 v37, v37
	v_fma_f32 v38, v48, s29, -v25
	v_fma_f32 v39, v48, s29, -v24
	v_exp_f32_e32 v38, v38
	v_exp_f32_e32 v39, v39
	v_and_b32_e32 v35, 0xffff0000, v56
	v_pk_mul_f32 v[34:35], v[36:37], v[34:35]
	v_lshlrev_b32_e32 v36, 16, v57
	v_and_b32_e32 v37, 0xffff0000, v57
	v_pk_mul_f32 v[36:37], v[38:39], v[36:37]
	v_fma_f32 v38, v48, s29, -v23
	v_fma_f32 v39, v48, s29, -v22
	v_cvt_pk_bf16_f32 v34, v34, v35
	v_exp_f32_e32 v38, v38
	v_exp_f32_e32 v39, v39
	v_cndmask_b32_e32 v35, 0, v34, vcc
	v_lshrrev_b32_e32 v34, 16, v34
	v_cmp_lt_i32_e32 vcc, 0, v46
	v_fma_f32 v44, v48, s29, -v21
	v_fma_f32 v45, v48, s29, -v20
	v_cndmask_b32_e32 v34, 0, v34, vcc
	v_perm_b32 v34, v34, v35, s97
	v_cvt_pk_bf16_f32 v35, v36, v37
	v_cmp_lt_i32_e32 vcc, 1, v46
	v_and_b32_e32 v43, 0xffff0000, v58
	v_exp_f32_e32 v44, v44
	v_exp_f32_e32 v45, v45
	v_cndmask_b32_e32 v36, 0, v35, vcc
	v_lshrrev_b32_e32 v35, 16, v35
	v_cmp_lt_i32_e32 vcc, 2, v46
	v_pk_mul_f32 v[38:39], v[38:39], v[42:43]
	v_lshlrev_b32_e32 v42, 16, v59
	v_cndmask_b32_e32 v35, 0, v35, vcc
	v_perm_b32 v35, v35, v36, s97
	v_cvt_pk_bf16_f32 v36, v38, v39
	v_cmp_lt_i32_e32 vcc, 3, v46
	v_and_b32_e32 v43, 0xffff0000, v59
	v_pk_mul_f32 v[42:43], v[44:45], v[42:43]
	v_cndmask_b32_e32 v37, 0, v36, vcc
	v_lshrrev_b32_e32 v36, 16, v36
	v_cmp_lt_i32_e32 vcc, 4, v46
	s_mov_b64 s[78:79], 0
	s_nop 0
	v_cndmask_b32_e32 v36, 0, v36, vcc
	v_perm_b32 v36, v36, v37, s97
	v_cvt_pk_bf16_f32 v37, v42, v43
	v_cmp_lt_i32_e32 vcc, 5, v46
	s_cmp_lg_u64 s[42:43], 0
	s_cbranch_scc1 .Lscan_w47_1
	s_waitcnt vmcnt(14)
	s_branch .Lscan_wdone_1
.Lscan_w47_1:
	s_waitcnt vmcnt(11)
.Lscan_wdone_1:
	v_lshlrev_b32_e32 v42, 16, v70
	v_and_b32_e32 v43, 0xffff0000, v70
	v_cndmask_b32_e32 v38, 0, v37, vcc
	v_lshrrev_b32_e32 v37, 16, v37
	v_cmp_lt_i32_e32 vcc, 6, v46
	s_nop 1
	v_cndmask_b32_e32 v37, 0, v37, vcc
	v_perm_b32 v37, v37, v38, s97
	ds_write_b128 v33, v[34:37]
	v_add_u32_e32 v33, 32, v29
	v_lshlrev_b32_e32 v34, 8, v33
	v_add3_u32 v46, v30, v34, 0
	v_add_u32_e32 v34, 0x10000, v46
	ds_write_b128 v34, v[76:79]
	ds_write_b128 v46, v[64:67] offset:32768
	v_lshlrev_b32_e32 v36, 16, v68
	v_and_b32_e32 v37, 0xffff0000, v68
	v_sub_u32_e32 v33, v33, v26
	v_cmp_lt_i32_e32 vcc, -1, v33
	v_fma_f32 v34, v49, s29, -v28
	v_fma_f32 v35, v49, s29, -v27
	v_exp_f32_e32 v34, v34
	v_exp_f32_e32 v35, v35
	v_fma_f32 v38, v49, s29, -v25
	v_fma_f32 v39, v49, s29, -v24
	v_exp_f32_e32 v38, v38
	v_exp_f32_e32 v39, v39
	v_pk_mul_f32 v[34:35], v[34:35], v[36:37]
	v_lshlrev_b32_e32 v36, 16, v69
	v_and_b32_e32 v37, 0xffff0000, v69
	v_pk_mul_f32 v[36:37], v[38:39], v[36:37]
	v_fma_f32 v38, v49, s29, -v23
	v_fma_f32 v39, v49, s29, -v22
	v_cvt_pk_bf16_f32 v34, v34, v35
	v_exp_f32_e32 v38, v38
	v_exp_f32_e32 v39, v39
	v_cndmask_b32_e32 v35, 0, v34, vcc
	v_cmp_lt_i32_e32 vcc, 0, v33
	v_fma_f32 v44, v49, s29, -v21
	v_fma_f32 v45, v49, s29, -v20
	v_cndmask_b32_sdwa v34, v1, v34, vcc dst_sel:DWORD dst_unused:UNUSED_PAD src0_sel:DWORD src1_sel:WORD_1
	v_perm_b32 v34, v34, v35, s97
	v_cvt_pk_bf16_f32 v35, v36, v37
	v_cmp_lt_i32_e32 vcc, 1, v33
	v_exp_f32_e32 v44, v44
	v_exp_f32_e32 v45, v45
	v_cndmask_b32_e32 v36, 0, v35, vcc
	v_cmp_lt_i32_e32 vcc, 2, v33
	v_pk_mul_f32 v[38:39], v[38:39], v[42:43]
	v_lshlrev_b32_e32 v42, 16, v71
	v_cndmask_b32_sdwa v35, v1, v35, vcc dst_sel:DWORD dst_unused:UNUSED_PAD src0_sel:DWORD src1_sel:WORD_1
	v_perm_b32 v35, v35, v36, s97
	v_cvt_pk_bf16_f32 v36, v38, v39
	v_cmp_lt_i32_e32 vcc, 3, v33
	v_and_b32_e32 v43, 0xffff0000, v71
	v_pk_mul_f32 v[42:43], v[44:45], v[42:43]
	v_cndmask_b32_e32 v37, 0, v36, vcc
	v_cmp_lt_i32_e32 vcc, 4, v33
	s_nop 1
	v_cndmask_b32_sdwa v36, v1, v36, vcc dst_sel:DWORD dst_unused:UNUSED_PAD src0_sel:DWORD src1_sel:WORD_1
	v_perm_b32 v36, v36, v37, s97
	v_cvt_pk_bf16_f32 v37, v42, v43
	v_cmp_lt_i32_e32 vcc, 5, v33
	s_nop 1
	v_cndmask_b32_e32 v38, 0, v37, vcc
	v_cmp_lt_i32_e32 vcc, 6, v33
	s_nop 1
	v_cndmask_b32_sdwa v33, v1, v37, vcc dst_sel:DWORD dst_unused:UNUSED_PAD src0_sel:DWORD src1_sel:WORD_1
	v_perm_b32 v37, v33, v38, s97
	ds_write_b128 v46, v[34:37]

; DI void ssd_scan_phase(bf16_t* P, const bf16_t* BT, const bf16_t* Cc, const bf16_t* CB, const float* dt, const float* acs,
;                        const float* cw, const float* cb, const float* Dp, char* lds, bool dry, int mode, float* Sbuf) {
;     ...
;         for (int j = 0; j < 4; ++j) {
;           const int r = r0 + 32 * j;
;           *(u32x4*)(sBT + swz128(r, cch)) = rB[j];
.LBB0_1058:
	v_add_u32_e32 v34, 64, v29
	v_lshl_add_u32 v33, v34, 8, v30
	v_add_u32_e32 v33, 0, v33
	v_add_u32_e32 v35, 0x10000, v33
	s_and_b64 vcc, exec, s[56:57]
	s_mov_b64 s[78:79], -1
	s_cmp_lg_u64 s[42:43], 0
	s_cbranch_scc1 .Lscan_w47_2
	s_waitcnt vmcnt(11)
	s_branch .Lscan_wdone_2
.Lscan_w47_2:
	s_waitcnt vmcnt(8)
.Lscan_wdone_2:
	ds_write_b128 v35, v[92:95]
	s_cbranch_vccz .LBB0_1061
	s_andn2_b64 vcc, exec, s[78:79]
	s_cbranch_vccz .LBB0_1062

; DI u32x4 pack8(const float (&f)[8]) { u32x4 r; r[0] = pk2(f[0], f[1]); r[1] = pk2(f[2], f[3]); r[2] = pk2(f[4], f[5]); r[3] = pk2(f[6], f[7]); return r; }
; DI void ssd_scan_phase(bf16_t* P, const bf16_t* BT, const bf16_t* Cc, const bf16_t* CB, const float* dt, const float* acs,
;                        const float* cw, const float* cb, const float* Dp, char* lds, bool dry, int mode, float* Sbuf) {
;     ...
;           if (mode == 0) {
;             *(u32x4*)(sC + swz128(r, cch)) = rC[j];
;             float f[8]; unpack8(rCB[j], f);
;             const float el = cAcs[r] * L2E;
;             const int lim = r - cch * 8;
; #pragma unroll
;             for (int e = 0; e < 8; ++e) f[e] = (e <= lim) ? f[e] * __builtin_amdgcn_exp2f(el - as[e]) : 0.f;
;             *(u32x4*)(sCBL + swz128(r, cch)) = pack8(f);
;           }
;         }
.LBB0_1061:
	ds_write_b128 v33, v[72:75] offset:32768
	v_sub_u32_e32 v46, v34, v26
	v_lshlrev_b32_e32 v34, 16, v80
	v_cmp_lt_i32_e32 vcc, -1, v46
	v_lshlrev_b32_e32 v42, 16, v82
	v_fma_f32 v35, v50, s29, -v28
	v_fma_f32 v37, v50, s29, -v27
	v_exp_f32_e32 v36, v35
	v_exp_f32_e32 v37, v37
	v_fma_f32 v38, v50, s29, -v25
	v_fma_f32 v39, v50, s29, -v24
	v_exp_f32_e32 v38, v38
	v_exp_f32_e32 v39, v39
	v_and_b32_e32 v35, 0xffff0000, v80
	v_pk_mul_f32 v[34:35], v[36:37], v[34:35]
	v_lshlrev_b32_e32 v36, 16, v81
	v_and_b32_e32 v37, 0xffff0000, v81
	v_pk_mul_f32 v[36:37], v[38:39], v[36:37]
	v_fma_f32 v38, v50, s29, -v23
	v_fma_f32 v39, v50, s29, -v22
	v_cvt_pk_bf16_f32 v34, v34, v35
	v_exp_f32_e32 v38, v38
	v_exp_f32_e32 v39, v39
	v_cndmask_b32_e32 v35, 0, v34, vcc
	v_lshrrev_b32_e32 v34, 16, v34
	v_cmp_lt_i32_e32 vcc, 0, v46
	v_fma_f32 v44, v50, s29, -v21
	v_fma_f32 v45, v50, s29, -v20
	v_cndmask_b32_e32 v34, 0, v34, vcc
	v_perm_b32 v34, v34, v35, s97
	v_cvt_pk_bf16_f32 v35, v36, v37
	v_cmp_lt_i32_e32 vcc, 1, v46
	v_and_b32_e32 v43, 0xffff0000, v82
	v_exp_f32_e32 v44, v44
	v_exp_f32_e32 v45, v45
	v_cndmask_b32_e32 v36, 0, v35, vcc
	v_lshrrev_b32_e32 v35, 16, v35
	v_cmp_lt_i32_e32 vcc, 2, v46
	v_pk_mul_f32 v[38:39], v[38:39], v[42:43]
	v_lshlrev_b32_e32 v42, 16, v83
	v_cndmask_b32_e32 v35, 0, v35, vcc
	v_perm_b32 v35, v35, v36, s97
	v_cvt_pk_bf16_f32 v36, v38, v39
	v_cmp_lt_i32_e32 vcc, 3, v46
	v_and_b32_e32 v43, 0xffff0000, v83
	v_pk_mul_f32 v[42:43], v[44:45], v[42:43]
	v_cndmask_b32_e32 v37, 0, v36, vcc
	v_lshrrev_b32_e32 v36, 16, v36
	v_cmp_lt_i32_e32 vcc, 4, v46
	v_add_u32_e32 v29, 0x60, v29
	s_nop 0
	v_cndmask_b32_e32 v36, 0, v36, vcc
	v_perm_b32 v36, v36, v37, s97
	v_cvt_pk_bf16_f32 v37, v42, v43
	v_cmp_lt_i32_e32 vcc, 5, v46
	s_nop 1
	v_cndmask_b32_e32 v38, 0, v37, vcc
	v_lshrrev_b32_e32 v37, 16, v37
	v_cmp_lt_i32_e32 vcc, 6, v46
	s_nop 1
	v_cndmask_b32_e32 v37, 0, v37, vcc
	v_perm_b32 v37, v37, v38, s97
	ds_write_b128 v33, v[34:37]
	v_lshlrev_b32_e32 v33, 8, v29
	v_add3_u32 v33, v30, v33, 0
	v_add_u32_e32 v30, 0x10000, v33
	s_cmp_lg_u64 s[42:43], 0
	s_cbranch_scc1 .Lscan_w47_3
	s_waitcnt vmcnt(8)
	s_branch .Lscan_wdone_3

; DI u32x4 pack8(const float (&f)[8]) { u32x4 r; r[0] = pk2(f[0], f[1]); r[1] = pk2(f[2], f[3]); r[2] = pk2(f[4], f[5]); r[3] = pk2(f[6], f[7]); return r; }
; DI void ssd_scan_phase(bf16_t* P, const bf16_t* BT, const bf16_t* Cc, const bf16_t* CB, const float* dt, const float* acs,
;                        const float* cw, const float* cb, const float* Dp, char* lds, bool dry, int mode, float* Sbuf) {
;     ...
;         for (int j = 0; j < 4; ++j) {
;           const int r = r0 + 32 * j;
;           *(u32x4*)(sBT + swz128(r, cch)) = rB[j];
;           if (mode == 0) {
;             *(u32x4*)(sC + swz128(r, cch)) = rC[j];
;             float f[8]; unpack8(rCB[j], f);
;             const float el = cAcs[r] * L2E;
;             const int lim = r - cch * 8;
; #pragma unroll
;             for (int e = 0; e < 8; ++e) f[e] = (e <= lim) ? f[e] * __builtin_amdgcn_exp2f(el - as[e]) : 0.f;
;             *(u32x4*)(sCBL + swz128(r, cch)) = pack8(f);
;           }
;         }
.Lscan_wdone_3:
	ds_write_b128 v30, v[104:107]
	ds_write_b128 v33, v[84:87] offset:32768
	v_sub_u32_e32 v35, v29, v26
	v_and_b32_e32 v29, 0xffff0000, v88
	v_cmp_lt_i32_e32 vcc, -1, v35
	v_fma_f32 v26, v51, s29, -v28
	v_fma_f32 v27, v51, s29, -v27
	v_exp_f32_e32 v26, v26
	v_exp_f32_e32 v27, v27
	v_fma_f32 v25, v51, s29, -v25
	v_fma_f32 v24, v51, s29, -v24
	v_exp_f32_e32 v30, v25
	v_exp_f32_e32 v31, v24
	v_lshlrev_b32_e32 v28, 16, v88
	v_pk_mul_f32 v[24:25], v[26:27], v[28:29]
	v_lshlrev_b32_e32 v26, 16, v89
	v_and_b32_e32 v27, 0xffff0000, v89
	v_fma_f32 v23, v51, s29, -v23
	v_fma_f32 v22, v51, s29, -v22
	v_fma_f32 v21, v51, s29, -v21
	v_fma_f32 v20, v51, s29, -v20
	v_pk_mul_f32 v[26:27], v[30:31], v[26:27]
	v_exp_f32_e32 v28, v23
	v_exp_f32_e32 v29, v22
	v_exp_f32_e32 v30, v21
	v_exp_f32_e32 v31, v20
	v_lshlrev_b32_e32 v22, 16, v90
	v_and_b32_e32 v23, 0xffff0000, v90
	v_lshlrev_b32_e32 v20, 16, v91
	v_and_b32_e32 v21, 0xffff0000, v91
	v_pk_mul_f32 v[22:23], v[28:29], v[22:23]
	v_pk_mul_f32 v[28:29], v[30:31], v[20:21]
	v_cvt_pk_bf16_f32 v20, v24, v25
	v_cndmask_b32_e32 v21, 0, v20, vcc
	v_cmp_lt_i32_e32 vcc, 0, v35
	v_cvt_pk_bf16_f32 v22, v22, v23
	s_nop 0
	v_cndmask_b32_sdwa v20, v1, v20, vcc dst_sel:DWORD dst_unused:UNUSED_PAD src0_sel:DWORD src1_sel:WORD_1
	v_perm_b32 v20, v20, v21, s97
	v_cvt_pk_bf16_f32 v21, v26, v27
	v_cmp_lt_i32_e32 vcc, 1, v35
	s_nop 1
	v_cndmask_b32_e32 v24, 0, v21, vcc
	v_cmp_lt_i32_e32 vcc, 2, v35
	s_nop 1
	v_cndmask_b32_sdwa v21, v1, v21, vcc dst_sel:DWORD dst_unused:UNUSED_PAD src0_sel:DWORD src1_sel:WORD_1
	v_cmp_lt_i32_e32 vcc, 3, v35
	v_perm_b32 v21, v21, v24, s97
	s_nop 0
	v_cndmask_b32_e32 v23, 0, v22, vcc
	v_cmp_lt_i32_e32 vcc, 4, v35
	s_nop 1
	v_cndmask_b32_sdwa v22, v1, v22, vcc dst_sel:DWORD dst_unused:UNUSED_PAD src0_sel:DWORD src1_sel:WORD_1
	v_perm_b32 v22, v22, v23, s97
	v_cvt_pk_bf16_f32 v23, v28, v29
	v_cmp_lt_i32_e32 vcc, 5, v35
	s_nop 1
	v_cndmask_b32_e32 v24, 0, v23, vcc
	v_cmp_lt_i32_e32 vcc, 6, v35
	s_nop 1
	v_cndmask_b32_sdwa v23, v1, v23, vcc dst_sel:DWORD dst_unused:UNUSED_PAD src0_sel:DWORD src1_sel:WORD_1
	v_perm_b32 v23, v23, v24, s97
	ds_write_b128 v33, v[20:23]
	s_cbranch_execnz .LBB0_1060

; DI void ssd_scan_phase(bf16_t* P, const bf16_t* BT, const bf16_t* Cc, const bf16_t* CB, const float* dt, const float* acs,
;                        const float* cw, const float* cb, const float* Dp, char* lds, bool dry, int mode, float* Sbuf) {
;     ...
;       float nacs = 0.f, ndt = 0.f;
;       tsum += tchA + tchB;
;       if (c + 2 < c1) {
;         const size_t cb2 = cbi0 + (size_t)(c + 2) * 65536;
;         const int tl = tid & 255;
;         if (mode == 0 || tid >= 256) tchA = *(const unsigned*)((tid < 256 ? Cc : BT) + cb2 + tl * 64);
;         const bf16_t* rowp = P + (t0 + 256 + (tid & 127)) * 5120 + pcol + ((tid < 384) ? 2048 : 0);
;         if (mode == 0 || (tid >= 256 && tid < 384)) tchB = *(const unsigned*)((tid < 256) ? (CB + cb2 + tl * 64) : rowp);
;       }
;       if (c + 1 < c1) {
;         if (c + 2 < c1 && tid < 128) { nacs = (acs + (t0 + 256) * 32 + hh)[tid * 32]; ndt = (dt + (t0 + 256) * 32 + hh)[tid * 32]; }
.LBB0_1082:
	s_or_b64 exec, exec, s[78:79]
	s_waitcnt vmcnt(0)
	s_add_i32 s89, s80, 1
	s_cmp_lt_i32 s89, s69
	s_cselect_b64 s[82:83], -1, 0
	s_cmp_ge_i32 s89, s69
	v_ashrrev_i32_e32 v171, 31, v170
	s_cselect_b64 s[78:79], -1, 0
	v_lshl_add_u64 v[172:173], v[170:171], 0, s[70:71]
	v_mov_b32_e32 v171, 0
	s_and_b64 vcc, exec, s[78:79]
	s_cbranch_vccnz .LBB0_1100
	s_add_i32 s80, s80, 2
	s_cmp_lt_i32 s80, s69
	s_cselect_b64 s[80:81], -1, 0
	s_and_b64 vcc, s[48:49], s[80:81]
	v_mov_b32_e32 v196, 0
	v_mov_b32_e32 v171, 0
	s_and_saveexec_b64 s[80:81], vcc
	s_cbranch_execz .LBB0_1085
	v_lshlrev_b64 v[20:21], 7, v[172:173]
	s_mov_b64 vcc, 0x8000
	v_lshl_add_u64 v[20:21], v[20:21], 0, vcc
	v_lshl_add_u64 v[22:23], v[164:165], 0, v[20:21]
	v_lshl_add_u64 v[20:21], v[166:167], 0, v[20:21]
	global_load_dword v171, v[22:23], off
	global_load_dword v196, v[20:21], off

; #define MFMA(a, b, c) __builtin_amdgcn_mfma_f32_32x32x16_bf16((a), (b), (c), 0, 0, 0)
; DI float bflo(unsigned u) { return __uint_as_float(u << 16); }
; DI float bfhi(unsigned u) { return __uint_as_float(u & 0xffff0000u); }
; DI float silu(float x) { return x * __builtin_amdgcn_rcpf(1.f + __expf(-x)); }
; DI void ssd_scan_phase(bf16_t* P, const bf16_t* BT, const bf16_t* Cc, const bf16_t* CB, const float* dt, const float* acs,
;                        const float* cw, const float* cb, const float* Dp, char* lds, bool dry, int mode, float* Sbuf) {
;     ...
;       if (wave < 4) {
;        if (mode == 0) {
;         const int lt = wave;
;         f32x16 ad, ao;
; #pragma unroll
;         for (int i = 0; i < 16; ++i) { ad[i] = 0.f; ao[i] = 0.f; }
;         const char* stb = sSt + (c & 1) * 8192;
; #pragma unroll
;         for (int kk = 0; kk < 8; ++kk) {
;           const bf16x8 yf = *(const bf16x8*)(sCBL + swz128(32 * lt + lq, 2 * kk + hq));
;           const bf16x8 xf = *(const bf16x8*)(sXdt + swz128(lq, 2 * kk + hq));
;           ad = MFMA(xf, yf, ad);
;           const bf16x8 yf2 = *(const bf16x8*)(sC + swz128(32 * lt + lq, 2 * kk + hq));
;           const bf16x8 xf2 = *(const bf16x8*)(stb + swz128(lq, 2 * kk + hq));
;           ao = MFMA(xf2, yf2, ao);
;         }
;         const int l = 32 * lt + l31;
;         const float eo = __expf(cAcs[l]);
;         bf16_t* Zq = P + t0 * 5120 + pcol;
; #pragma unroll
;         for (int gi = 0; gi < 4; ++gi) {
;           const int p0 = 8 * gi + 4 * h;
;           const u32x2 xsv = *(const u32x2*)(sXs + l * 80 + p0 * 2);
;           const u32x2 zv = cz[gi];
;           const float xs0 = bflo(xsv[0]), xs1 = bfhi(xsv[0]), xs2 = bflo(xsv[1]), xs3 = bfhi(xsv[1]);
;           const float z0 = bflo(zv[0]), z1 = bfhi(zv[0]), z2 = bflo(zv[1]), z3 = bfhi(zv[1]);
;           const float y0 = (ad[4 * gi] + eo * ao[4 * gi] + Dh * xs0) * silu(z0);
.LBB0_1101:
	s_waitcnt lgkmcnt(0)
	s_barrier
	v_mov_b32_e32 v197, v133
	v_mov_b32_e32 v174, v175
	s_and_saveexec_b64 s[80:81], s[40:41]
	s_xor_b64 s[80:81], exec, s[80:81]
	s_cbranch_execz .LBB0_1107
	s_and_b64 vcc, exec, s[56:57]
	s_cbranch_vccnz .LBB0_1106
	s_andn2_b64 vcc, exec, s[82:83]
	v_bitop3_b32 v20, v174, v197, 15 bitop3:0x6c
	v_lshlrev_b32_e32 v199, 8, v174
	v_lshlrev_b32_e32 v24, 4, v20
	v_add_lshl_u32 v198, v174, v183, 8
	s_add_i32 s91, 0, 0x18000
	s_lshl_b32 s90, s90, 13
	s_add_i32 s90, s90, 0
	s_add_i32 s90, s90, 0x1c000
	v_add_u32_e32 v250, v24, v198
	v_add_u32_e32 v251, v24, v199
	v_add_u32_e32 v230, s90, v251
	v_add_u32_e32 v251, s91, v251
	ds_read_b128 v[20:23], v250
	ds_read_b128 v[24:27], v251
	ds_read_b128 v[36:39], v250 offset:32768
	ds_read_b128 v[40:43], v230
	v_xor_b32_e32 v231, 0x20, v250
	ds_read_b128 v[222:225], v231
	v_xor_b32_e32 v231, 0x20, v251
	ds_read_b128 v[226:229], v231
	v_xor_b32_e32 v231, 0x20, v250
	ds_read_b128 v[234:237], v231 offset:32768
	v_xor_b32_e32 v231, 0x20, v230
	ds_read_b128 v[238:241], v231
	v_xor_b32_e32 v231, 0x40, v250
	ds_read_b128 v[242:245], v231
	v_xor_b32_e32 v231, 0x40, v251
	ds_read_b128 v[246:249], v231
	s_waitcnt lgkmcnt(8)
	v_mfma_f32_32x32x16_bf16 v[20:35], v[24:27], v[20:23], 0
	s_waitcnt lgkmcnt(6)
	v_mfma_f32_32x32x16_bf16 v[36:51], v[40:43], v[36:39], 0
	s_waitcnt lgkmcnt(4)
	v_mfma_f32_32x32x16_bf16 v[20:35], v[226:229], v[222:225], v[20:35]
	v_xor_b32_e32 v231, 0x40, v250
	ds_read_b128 v[222:225], v231 offset:32768
	v_xor_b32_e32 v231, 0x40, v230
	ds_read_b128 v[226:229], v231
	s_waitcnt lgkmcnt(4)
	v_mfma_f32_32x32x16_bf16 v[36:51], v[238:241], v[234:237], v[36:51]
	v_xor_b32_e32 v231, 0x60, v250
	ds_read_b128 v[234:237], v231
	v_xor_b32_e32 v231, 0x60, v251
	ds_read_b128 v[238:241], v231
	s_waitcnt lgkmcnt(4)
	v_mfma_f32_32x32x16_bf16 v[20:35], v[246:249], v[242:245], v[20:35]
	v_xor_b32_e32 v231, 0x60, v250
	ds_read_b128 v[242:245], v231 offset:32768
	v_xor_b32_e32 v231, 0x60, v230
	ds_read_b128 v[246:249], v231
	s_waitcnt lgkmcnt(4)
	v_mfma_f32_32x32x16_bf16 v[36:51], v[226:229], v[222:225], v[36:51]
	v_xor_b32_e32 v231, 0x80, v250
	ds_read_b128 v[222:225], v231
	v_xor_b32_e32 v231, 0x80, v251
	ds_read_b128 v[226:229], v231
	s_waitcnt lgkmcnt(4)
	v_mfma_f32_32x32x16_bf16 v[20:35], v[238:241], v[234:237], v[20:35]
	v_xor_b32_e32 v231, 0x80, v250
	ds_read_b128 v[234:237], v231 offset:32768
	v_xor_b32_e32 v231, 0x80, v230
	ds_read_b128 v[238:241], v231
	s_waitcnt lgkmcnt(4)
	v_mfma_f32_32x32x16_bf16 v[36:51], v[246:249], v[242:245], v[36:51]
	v_xor_b32_e32 v231, 0xa0, v250
	ds_read_b128 v[242:245], v231
	v_xor_b32_e32 v231, 0xa0, v251
	ds_read_b128 v[246:249], v231
	s_waitcnt lgkmcnt(4)
	v_mfma_f32_32x32x16_bf16 v[20:35], v[226:229], v[222:225], v[20:35]
	v_xor_b32_e32 v231, 0xa0, v250
	ds_read_b128 v[222:225], v231 offset:32768
	v_xor_b32_e32 v231, 0xa0, v230
	ds_read_b128 v[226:229], v231
	s_waitcnt lgkmcnt(4)
	v_mfma_f32_32x32x16_bf16 v[36:51], v[238:241], v[234:237], v[36:51]
	v_xor_b32_e32 v231, 0xc0, v250
	ds_read_b128 v[234:237], v231
	v_xor_b32_e32 v231, 0xc0, v251
	ds_read_b128 v[238:241], v231
	s_waitcnt lgkmcnt(4)
	v_mfma_f32_32x32x16_bf16 v[20:35], v[246:249], v[242:245], v[20:35]
	v_xor_b32_e32 v231, 0xc0, v250
	ds_read_b128 v[242:245], v231 offset:32768
	v_xor_b32_e32 v231, 0xc0, v230
	ds_read_b128 v[246:249], v231
	s_waitcnt lgkmcnt(4)
	v_mfma_f32_32x32x16_bf16 v[36:51], v[226:229], v[222:225], v[36:51]
	v_xor_b32_e32 v231, 0xe0, v250
	ds_read_b128 v[222:225], v231
	v_xor_b32_e32 v231, 0xe0, v251
	ds_read_b128 v[226:229], v231
	s_waitcnt lgkmcnt(4)
	v_mfma_f32_32x32x16_bf16 v[20:35], v[238:241], v[234:237], v[20:35]
	v_xor_b32_e32 v231, 0xe0, v250
	ds_read_b128 v[234:237], v231 offset:32768
	v_xor_b32_e32 v231, 0xe0, v230
	ds_read_b128 v[238:241], v231
	v_lshl_add_u32 v174, v187, 2, s88
	ds_read_b32 v174, v174
	v_mov_b64_e32 v[198:199], s[72:73]
	v_mad_u64_u32 v[198:199], s[90:91], v172, s96, v[198:199]
	v_mad_i32_i24 v199, v173, s96, v199
	v_lshl_add_u64 v[172:173], v[198:199], 0, v[0:1]
	s_waitcnt lgkmcnt(5)
	v_mfma_f32_32x32x16_bf16 v[36:51], v[246:249], v[242:245], v[36:51]
	s_waitcnt lgkmcnt(3)
	v_mfma_f32_32x32x16_bf16 v[20:35], v[226:229], v[222:225], v[20:35]
	s_waitcnt lgkmcnt(0)
	v_mul_f32_e32 v174, 0x3fb8aa3b, v174
	v_mfma_f32_32x32x16_bf16 v[36:51], v[238:241], v[234:237], v[36:51]
	v_exp_f32_e32 v174, v174
	v_lshlrev_b32_e32 v226, 16, v158
	v_and_b32_e32 v227, 0xffff0000, v158
	v_mul_f32_e32 v197, 0xbfb8aa3b, v226
	v_exp_f32_e32 v197, v197
	ds_read2_b64 v[222:225], v193 offset1:2
	s_nop 5
	v_pk_fma_f32 v[20:21], v[36:37], v[174:175], v[20:21] op_sel_hi:[1,0,1]
	v_mul_f32_e32 v36, 0xbfb8aa3b, v227
	v_exp_f32_e32 v36, v36
	v_add_f32_e32 v197, 1.0, v197
	v_rcp_f32_e32 v228, v197
	s_waitcnt lgkmcnt(0)
; DI unsigned pk2(float lo, float hi) { f32x2 v = {lo, hi}; bf2_t r = __builtin_convertvector(v, bf2_t); return __builtin_bit_cast(unsigned, r); }
; DI float bflo(unsigned u) { return __uint_as_float(u << 16); }
; DI float bfhi(unsigned u) { return __uint_as_float(u & 0xffff0000u); }
; DI float silu(float x) { return x * __builtin_amdgcn_rcpf(1.f + __expf(-x)); }
; DI void ssd_scan_phase(bf16_t* P, const bf16_t* BT, const bf16_t* Cc, const bf16_t* CB, const float* dt, const float* acs,
;                        const float* cw, const float* cb, const float* Dp, char* lds, bool dry, int mode, float* Sbuf) {
;     ...
; #pragma unroll
;         for (int gi = 0; gi < 4; ++gi) {
;           const int p0 = 8 * gi + 4 * h;
;           const u32x2 xsv = *(const u32x2*)(sXs + l * 80 + p0 * 2);
;           const u32x2 zv = cz[gi];
;           const float xs0 = bflo(xsv[0]), xs1 = bfhi(xsv[0]), xs2 = bflo(xsv[1]), xs3 = bfhi(xsv[1]);
;           const float z0 = bflo(zv[0]), z1 = bfhi(zv[0]), z2 = bflo(zv[1]), z3 = bfhi(zv[1]);
;           const float y0 = (ad[4 * gi] + eo * ao[4 * gi] + Dh * xs0) * silu(z0);
;           const float y1 = (ad[4 * gi + 1] + eo * ao[4 * gi + 1] + Dh * xs1) * silu(z1);
;           const float y2 = (ad[4 * gi + 2] + eo * ao[4 * gi + 2] + Dh * xs2) * silu(z2);
;           const float y3 = (ad[4 * gi + 3] + eo * ao[4 * gi + 3] + Dh * xs3) * silu(z3);
;           u32x2 ov; ov[0] = pk2(y0, y1); ov[1] = pk2(y2, y3);
;           if (!dry) *(u32x2*)(Zq + zoff + 8 * gi) = ov;
;         }
;         if (c + 1 < c1) {
; #pragma unroll
;           for (int gi = 0; gi < 4; ++gi) cz[gi] = *(const u32x2*)(Zq + 128 * 5120 + zoff + 8 * gi);
;         }
	v_lshlrev_b32_e32 v198, 16, v222
	v_add_f32_e32 v36, 1.0, v36
	v_rcp_f32_e32 v229, v36
	v_and_b32_e32 v199, 0xffff0000, v222
	v_pk_fma_f32 v[20:21], v[156:157], v[198:199], v[20:21]
	v_lshlrev_b32_e32 v198, 16, v159
	v_pk_mul_f32 v[36:37], v[228:229], v[226:227]
	v_and_b32_e32 v199, 0xffff0000, v159
	v_pk_mul_f32 v[20:21], v[36:37], v[20:21]
	v_lshlrev_b32_e32 v36, 16, v223
	v_and_b32_e32 v37, 0xffff0000, v223
	v_pk_fma_f32 v[22:23], v[38:39], v[174:175], v[22:23] op_sel_hi:[1,0,1]
	v_mul_f32_e32 v197, 0xbfb8aa3b, v198
	v_pk_fma_f32 v[22:23], v[156:157], v[36:37], v[22:23]
	v_mul_f32_e32 v36, 0xbfb8aa3b, v199
	v_exp_f32_e32 v197, v197
	v_exp_f32_e32 v36, v36
	v_lshlrev_b32_e32 v38, 16, v160
	v_and_b32_e32 v39, 0xffff0000, v160
	v_add_f32_e32 v197, 1.0, v197
	v_add_f32_e32 v36, 1.0, v36
	v_rcp_f32_e32 v222, v197
	v_rcp_f32_e32 v223, v36
	v_pk_fma_f32 v[24:25], v[40:41], v[174:175], v[24:25] op_sel_hi:[1,0,1]
	v_mul_f32_e32 v197, 0xbfb8aa3b, v38
	v_exp_f32_e32 v197, v197
	v_pk_mul_f32 v[36:37], v[222:223], v[198:199]
	v_pk_fma_f32 v[26:27], v[42:43], v[174:175], v[26:27] op_sel_hi:[1,0,1]
	v_pk_mul_f32 v[22:23], v[36:37], v[22:23]
	v_lshlrev_b32_e32 v36, 16, v224
	v_and_b32_e32 v37, 0xffff0000, v224
	v_pk_fma_f32 v[24:25], v[156:157], v[36:37], v[24:25]
	v_mul_f32_e32 v36, 0xbfb8aa3b, v39
	v_exp_f32_e32 v36, v36
	v_add_f32_e32 v197, 1.0, v197
	v_rcp_f32_e32 v198, v197
	v_cvt_pk_bf16_f32 v20, v20, v21
	v_add_f32_e32 v36, 1.0, v36
	v_rcp_f32_e32 v199, v36
	v_cvt_pk_bf16_f32 v21, v22, v23
	global_store_dwordx2 v[172:173], v[20:21], off
	ds_read2_b64 v[20:23], v193 offset0:4 offset1:6
	v_pk_mul_f32 v[36:37], v[198:199], v[38:39]
	v_lshlrev_b32_e32 v38, 16, v161
	v_pk_mul_f32 v[24:25], v[36:37], v[24:25]
	v_lshlrev_b32_e32 v36, 16, v225
	v_and_b32_e32 v37, 0xffff0000, v225
	v_and_b32_e32 v39, 0xffff0000, v161
	v_mul_f32_e32 v40, 0xbfb8aa3b, v38
	v_pk_fma_f32 v[26:27], v[156:157], v[36:37], v[26:27]
	v_mul_f32_e32 v36, 0xbfb8aa3b, v39
	v_exp_f32_e32 v40, v40
	v_exp_f32_e32 v36, v36
	v_cvt_pk_bf16_f32 v24, v24, v25
	v_pk_fma_f32 v[28:29], v[44:45], v[174:175], v[28:29] op_sel_hi:[1,0,1]
	v_add_f32_e32 v40, 1.0, v40
	v_add_f32_e32 v36, 1.0, v36
	v_rcp_f32_e32 v40, v40
	v_rcp_f32_e32 v41, v36
	v_pk_fma_f32 v[30:31], v[46:47], v[174:175], v[30:31] op_sel_hi:[1,0,1]
	v_pk_mul_f32 v[36:37], v[40:41], v[38:39]
	s_nop 0
	v_pk_mul_f32 v[26:27], v[36:37], v[26:27]
	s_nop 0
	v_cvt_pk_bf16_f32 v25, v26, v27
	v_lshlrev_b32_e32 v26, 16, v162
	global_store_dwordx2 v[172:173], v[24:25], off offset:16
	s_waitcnt lgkmcnt(0)
	v_lshlrev_b32_e32 v24, 16, v20
	v_and_b32_e32 v25, 0xffff0000, v20
	v_mul_f32_e32 v20, 0xbfb8aa3b, v26
	v_exp_f32_e32 v20, v20
	v_and_b32_e32 v27, 0xffff0000, v162
	v_pk_fma_f32 v[24:25], v[156:157], v[24:25], v[28:29]
	v_add_f32_e32 v20, 1.0, v20
	v_rcp_f32_e32 v36, v20
	v_mul_f32_e32 v20, 0xbfb8aa3b, v27
	v_exp_f32_e32 v20, v20
	s_nop 0
	v_add_f32_e32 v20, 1.0, v20
	v_rcp_f32_e32 v37, v20
	v_lshlrev_b32_e32 v20, 16, v21
	v_and_b32_e32 v21, 0xffff0000, v21
	v_pk_fma_f32 v[20:21], v[156:157], v[20:21], v[30:31]
	v_pk_mul_f32 v[26:27], v[36:37], v[26:27]
	s_nop 0
	v_pk_mul_f32 v[24:25], v[26:27], v[24:25]
	v_lshlrev_b32_e32 v26, 16, v163
	v_and_b32_e32 v27, 0xffff0000, v163
	v_mul_f32_e32 v28, 0xbfb8aa3b, v26
	v_mul_f32_e32 v29, 0xbfb8aa3b, v27
	v_exp_f32_e32 v28, v28
	v_exp_f32_e32 v29, v29
	v_cvt_pk_bf16_f32 v24, v24, v25
	v_add_f32_e32 v28, 1.0, v28
	v_add_f32_e32 v29, 1.0, v29
	v_rcp_f32_e32 v28, v28
	v_rcp_f32_e32 v29, v29
	s_nop 0
	v_pk_mul_f32 v[26:27], v[28:29], v[26:27]
	s_nop 0
	v_pk_mul_f32 v[20:21], v[26:27], v[20:21]
	v_pk_fma_f32 v[28:29], v[48:49], v[174:175], v[32:33] op_sel_hi:[1,0,1]
	v_cvt_pk_bf16_f32 v25, v20, v21
	global_store_dwordx2 v[172:173], v[24:25], off offset:32
	v_lshlrev_b32_e32 v24, 16, v2
	v_lshlrev_b32_e32 v20, 16, v22
	v_and_b32_e32 v21, 0xffff0000, v22
	v_mul_f32_e32 v22, 0xbfb8aa3b, v24
	v_exp_f32_e32 v22, v22
	v_and_b32_e32 v25, 0xffff0000, v2
	v_pk_fma_f32 v[20:21], v[156:157], v[20:21], v[28:29]
	v_pk_fma_f32 v[28:29], v[50:51], v[174:175], v[34:35] op_sel_hi:[1,0,1]
	v_add_f32_e32 v22, 1.0, v22
	v_rcp_f32_e32 v26, v22
	v_mul_f32_e32 v22, 0xbfb8aa3b, v25
	v_exp_f32_e32 v22, v22
	s_nop 0
	v_add_f32_e32 v22, 1.0, v22
	v_rcp_f32_e32 v27, v22
	v_lshlrev_b32_e32 v22, 16, v23
	v_and_b32_e32 v23, 0xffff0000, v23
	v_pk_fma_f32 v[22:23], v[156:157], v[22:23], v[28:29]
	v_pk_mul_f32 v[24:25], v[26:27], v[24:25]
	s_nop 0
	v_pk_mul_f32 v[20:21], v[24:25], v[20:21]
	v_lshlrev_b32_e32 v24, 16, v3
	v_and_b32_e32 v25, 0xffff0000, v3
	v_mul_f32_e32 v26, 0xbfb8aa3b, v24
	v_mul_f32_e32 v27, 0xbfb8aa3b, v25
	v_exp_f32_e32 v26, v26
	v_exp_f32_e32 v27, v27
	v_cvt_pk_bf16_f32 v20, v20, v21
	v_add_f32_e32 v26, 1.0, v26
	v_add_f32_e32 v27, 1.0, v27
	v_rcp_f32_e32 v26, v26
	v_rcp_f32_e32 v27, v27
	s_nop 0
	v_pk_mul_f32 v[24:25], v[26:27], v[24:25]
	s_nop 0
	v_pk_mul_f32 v[22:23], v[24:25], v[22:23]
	s_nop 0
	v_cvt_pk_bf16_f32 v21, v22, v23
	global_store_dwordx2 v[172:173], v[20:21], off offset:48
	s_cbranch_vccnz .LBB0_1105
	s_mov_b64 s[82:83], 0x140000
	v_add_co_u32_e32 v20, vcc, 0x140000, v172
	v_lshl_add_u64 v[2:3], v[172:173], 0, s[82:83]
	s_nop 0
	v_addc_co_u32_e32 v21, vcc, 0, v173, vcc
	global_load_dwordx2 v[158:159], v[20:21], off
	global_load_dwordx2 v[160:161], v[2:3], off offset:16
	global_load_dwordx2 v[162:163], v[2:3], off offset:32
	s_nop 0
	global_load_dwordx2 v[2:3], v[2:3], off offset:48

; #define LDS_BARRIER() do { asm volatile("s_waitcnt lgkmcnt(0)" ::: "memory"); __builtin_amdgcn_s_barrier(); asm volatile("" ::: "memory"); } while (0)
; DI void ssd_scan_phase(bf16_t* P, const bf16_t* BT, const bf16_t* Cc, const bf16_t* CB, const float* dt, const float* acs,
;                        const float* cw, const float* cb, const float* Dp, char* lds, bool dry, int mode, float* Sbuf) {
;     ...
;       if (tid < 128) { sAcs[((c + 1) & 1) * 128 + tid] = racs; sDt[((c + 1) & 1) * 128 + tid] = rdt; }
;       racs = nacs; rdt = ndt;
;       LDS_BARRIER();
.LBB0_1109:
	s_or_b64 exec, exec, s[80:81]
	v_add_u32_e32 v20, 0x80, v170
	s_and_saveexec_b64 s[80:81], s[50:51]
	s_xor_b64 s[80:81], exec, s[80:81]
	v_add_u32_e32 v170, 0x80, v170
	s_andn2_saveexec_b64 s[80:81], s[80:81]
	s_cbranch_execz .LBB0_1113
	v_and_b32_e32 v21, 0x80, v20
	v_add_u32_e32 v21, v21, v127
	v_lshl_add_u32 v21, v21, 2, 0
	v_add_u32_e32 v22, 0x22c00, v21
	v_add_u32_e32 v21, 0x22800, v21
	v_mov_b32_e32 v170, v20
	ds_write_b32 v21, v194
	ds_write_b32 v22, v195
.LBB0_1113:
	s_or_b64 exec, exec, s[80:81]
	s_add_u32 s74, s74, 0x20000
	s_waitcnt lgkmcnt(0)
	s_barrier
	s_addc_u32 s75, s75, 0
	s_add_u32 s76, s76, 0x20000
	s_addc_u32 s77, s77, 0
	s_addk_i32 s85, 0x2000
	s_and_b64 vcc, exec, s[78:79]
	s_cbranch_vccnz .LBB0_1119
	s_cmp_lg_u64 s[56:57], 0
	s_cbranch_scc1 .Lscan_end_m1
	s_waitcnt vmcnt(16)
	s_branch .Lscan_end_done

; #define LDS_BARRIER() do { asm volatile("s_waitcnt lgkmcnt(0)" ::: "memory"); __builtin_amdgcn_s_barrier(); asm volatile("" ::: "memory"); } while (0)
; DI void ssd_scan_phase(bf16_t* P, const bf16_t* BT, const bf16_t* Cc, const bf16_t* CB, const float* dt, const float* acs,
;                        const float* cw, const float* cb, const float* Dp, char* lds, bool dry, int mode, float* Sbuf) {
;     ...
;       racs = nacs; rdt = ndt;
;       LDS_BARRIER();
;     }
.Lscan_end_done:
	v_mov_b32_e32 v194, v171
	v_mov_b32_e32 v195, v196
	s_mov_b32 s80, s89
	s_branch .LBB0_1054

; DI void run_phase(const Params& p, int ph, char* lds, bool dry) {
;     ...
;     case 2: {
;       if (!odd) {
;         bf16_t* cat = p.P + (size_t)T * 1280;
;         attn_phase(p.P, cat, p.ap_sinks + i * 8, lds);
;         pool_phase(p.P, cat, Wb + W_POOL, p.pool_scale + i * 512, lds);
;       } else {
;         ssd_cb_phase(p.P, p.H, p.H + (size_t)512 * 16384, p.CB, p.dt, p.acs, p.ssd_conv_w + (size_t)i * 4 * 3072, p.ssd_conv_b + i * 3072, p.ssd_A_log + i * 32, lds);
;       }
.LBB0_1122:
	s_andn2_b64 vcc, exec, s[0:1]
	s_movk_i32 s80, 0x280
	s_movk_i32 s81, 0xb00
	s_movk_i32 s82, 0x2c00
	s_cbranch_vccnz .LBB0_1160
	v_readlane_b32 s4, v255, 19
	v_readlane_b32 s5, v255, 20
	s_and_b64 vcc, exec, s[4:5]
	v_readlane_b32 s4, v252, 46
	v_readlane_b32 s5, v252, 47
	s_mov_b64 s[0:1], -1
	s_nop 0
	v_cndmask_b32_e64 v0, 0, 1, s[4:5]
	v_cmp_ne_u32_e64 s[18:19], 1, v0
	s_cbranch_vccz .LBB0_1136
	s_mov_b64 s[88:89], s[18:19]
	s_and_b64 vcc, exec, s[18:19]
	v_readlane_b32 s4, v253, 16
	s_waitcnt vmcnt(3)
	v_mov_b32_e32 v66, v200
	v_readlane_b32 s18, v253, 30
	v_readlane_b32 s19, v253, 31
	s_movk_i32 s79, 0x7f
	v_readlane_b32 s5, v253, 17
	v_readlane_b32 s6, v253, 18
	v_readlane_b32 s7, v253, 19
	v_readlane_b32 s8, v253, 20
	v_readlane_b32 s9, v253, 21
	v_readlane_b32 s10, v253, 22
	v_readlane_b32 s11, v253, 23
	v_readlane_b32 s12, v253, 24
	v_readlane_b32 s13, v253, 25
	v_readlane_b32 s14, v253, 26
	v_readlane_b32 s15, v253, 27
	v_readlane_b32 s16, v253, 28
	v_readlane_b32 s17, v253, 29
	s_cbranch_vccnz .LBB0_1135
; DI int otid() { int t = threadIdx.x; asm volatile("" : "+v"(t)); return t; }
; DI void ssd_cb_phase(const bf16_t* P, bf16_t* BT, bf16_t* Cc, bf16_t* CB, const float* dt, float* acs,
;                      const float* cw, const float* cb, const float* A_log, char* lds) {
;     ...
;   const int tid = otid(), lane = tid & 63, wave = tid >> 6, h = lane >> 5, l31 = lane & 31;
;   for (int item = blockIdx.x; item < 512; item += gridDim.x) {
;     const int g = item & 3, c = (item >> 2) & 63, b = item >> 8;
;     const size_t t0 = (size_t)b * SEQ + c * 128;
;     const int tin0 = c * 128;
;     bf16_t* BTi = BT + (size_t)item * 16384; bf16_t* Cci = Cc + (size_t)item * 16384; bf16_t* CBi = CB + (size_t)item * 16384;
;     float* sW = (float*)(lds + 65536);
;     u32x4 raw[4][4];
; #pragma unroll
;     for (int j = 0; j < 4; ++j) {
;       const int q = tid + 512 * j;
;       const int lb = q & 127, cb8 = q >> 7;
; #pragma unroll
;       for (int kk = 0; kk < 4; ++kk) raw[j][kk] = *(const u32x4*)(P + (t0 + lb - ((tin0 + lb - 3 + kk >= 0) ? (3 - kk) : 0)) * 5120 + 2048 + 2048 + g * 128 + cb8 * 8);
;     }
;     for (int q = tid; q < 1280; q += 512) { const int which = q / 640, r = q % 640, kk = r >> 7, col = 2048 + which * 512 + g * 128 + (r & 127); sW[q] = (kk < 4) ? cw[kk * 3072 + col] : cb[col]; }
	v_readlane_b32 s4, v255, 18
	s_mul_i32 s1, s4, 0xc000
	v_readlane_b32 s40, v253, 34
	s_mul_hi_u32 s0, s4, 0xc000
	v_readlane_b32 s41, v253, 35
	s_add_u32 s28, s40, s1
	s_mul_i32 s34, s4, 0xc00
	v_readlane_b32 s42, v253, 36
	s_addc_u32 s37, s41, s0
	s_lshl_b64 s[0:1], s[34:35], 2
	v_readlane_b32 s43, v253, 37
	s_add_u32 s70, s42, s0
	s_addc_u32 s71, s43, s1
	s_lshl_b32 s34, s4, 5
	v_readlane_b32 s46, v253, 40
	s_lshl_b64 s[0:1], s[34:35], 2
	v_lshlrev_b32_e32 v0, 3, v66
	s_add_u32 s30, s46, s0
	s_movk_i32 s0, 0x500
	s_waitcnt vmcnt(0)
	v_and_b32_e32 v2, 0x78, v0
	v_cmp_gt_i32_e32 vcc, s0, v66
	v_lshlrev_b32_e32 v0, 2, v2
	v_readlane_b32 s0, v255, 8
	v_readlane_b32 s47, v253, 41
	s_addc_u32 s31, s47, s1
	v_add_u32_e32 v73, s0, v0
	v_readlane_b32 s0, v255, 9
	v_ashrrev_i32_e32 v69, 6, v66
	v_lshlrev_b32_e32 v4, 8, v66
	v_add_u32_e32 v115, s0, v0
	v_readlane_b32 s0, v252, 44
	v_lshlrev_b32_e32 v0, 1, v2
	v_readlane_b32 s1, v252, 45
	v_and_b32_e32 v4, 0x1f00, v4
	v_add_u32_e32 v17, 0, v4
	v_lshl_add_u64 v[70:71], s[0:1], 0, v[0:1]
	v_lshlrev_b32_e32 v0, 13, v69
	v_and_b32_e32 v0, 0x6000, v0
	v_add_u32_e32 v117, v17, v0
	v_or_b32_e32 v0, v0, v4
	v_add_u32_e32 v67, 0x200, v66
	v_lshl_add_u64 v[74:75], s[20:21], 0, v[0:1]
	v_add_u32_e32 v0, 0x400, v66
	v_and_b32_e32 v21, 3, v66
	v_or_b32_e32 v21, 4, v21
	v_lshrrev_b32_e32 v68, 2, v66
	v_ashrrev_i32_e32 v80, 4, v0
	v_readlane_b32 s1, v255, 10
	s_add_i32 s72, 0, 0x10000
	v_lshlrev_b32_e32 v22, 5, v21
	v_and_b32_e32 v0, 3, v66
	v_or_b32_e32 v0, 8, v0
	v_add_u32_e32 v19, 0x600, v66
	v_add_u32_e32 v121, s1, v22
	v_add_u32_e32 v122, s72, v22
	v_bitop3_b32 v22, v21, v68, 15 bitop3:0x78
	v_lshl_or_b32 v86, v21, 10, v68
	v_lshlrev_b32_e32 v21, 5, v0
	v_add_u32_e32 v123, s1, v21
	v_add_u32_e32 v124, s72, v21
	v_bitop3_b32 v21, v0, v68, 15 bitop3:0x78
	v_lshl_or_b32 v88, v0, 10, v68
	v_and_b32_e32 v0, 3, v66
	v_or_b32_e32 v0, 12, v0
	v_ashrrev_i32_e32 v76, 4, v66
	v_ashrrev_i32_e32 v82, 4, v19
	v_lshlrev_b32_e32 v19, 5, v0
	v_add_u32_e32 v125, s1, v19
	v_add_u32_e32 v126, s72, v19
	v_bitop3_b32 v19, v0, v68, 15 bitop3:0x78
	v_lshl_or_b32 v90, v0, 10, v68
	v_xor_b32_e32 v0, v76, v66
	v_lshlrev_b32_e32 v0, 4, v0
	v_ashrrev_i32_e32 v78, 4, v67
	v_and_b32_e32 v0, 0xf0, v0
	v_add_u32_e32 v24, 0, v0
	v_xor_b32_e32 v0, v78, v66
	v_lshlrev_b32_e32 v0, 4, v0
	v_and_b32_e32 v0, 0xf0, v0
	v_add_u32_e32 v26, 0, v0
	v_xor_b32_e32 v0, v80, v66
	v_lshlrev_b32_e32 v0, 4, v0
	v_and_b32_e32 v0, 0xf0, v0
	v_readlane_b32 s44, v253, 38
	v_readlane_b32 s45, v253, 39
	v_readlane_b32 s48, v253, 42
	v_readlane_b32 s49, v253, 43
	v_readlane_b32 s50, v253, 44
	v_readlane_b32 s51, v253, 45
	v_readlane_b32 s52, v253, 46
	v_readlane_b32 s53, v253, 47
	v_and_b32_e32 v3, 63, v66
	v_bfe_u32 v12, v66, 5, 1
	v_and_b32_e32 v13, 15, v66
	v_add_u32_e32 v28, 0, v0
	v_xor_b32_e32 v0, v82, v66
	v_lshlrev_b32_e32 v72, 1, v3
	v_lshlrev_b32_e32 v0, 4, v0
	v_cmp_eq_u32_e64 s[42:43], 0, v3
	v_cmp_gt_u32_e64 s[44:45], 2, v3
	v_cmp_gt_u32_e64 s[46:47], 4, v3
	v_cmp_gt_u32_e64 s[48:49], 8, v3
	v_cmp_gt_u32_e64 s[50:51], 16, v3
	v_cmp_gt_u32_e64 s[52:53], 32, v3
	v_bitop3_b32 v3, v12, v13, 2 bitop3:0x36
	v_and_b32_e32 v0, 0xf0, v0
	v_lshlrev_b32_e32 v131, 4, v3
	v_bitop3_b32 v3, v12, v13, 4 bitop3:0x36
	v_ashrrev_i32_e32 v15, 7, v66
	v_and_b32_e32 v31, 3, v66
	v_add_u32_e32 v30, 0, v0
	v_bitop3_b32 v0, v12, v66, 15 bitop3:0x78
	v_lshlrev_b32_e32 v133, 4, v3
	v_bitop3_b32 v3, v12, v13, 6 bitop3:0x36
	v_lshlrev_b32_e32 v18, 2, v12
	v_lshlrev_b32_e32 v128, 4, v0
	v_or_b32_e32 v0, 1, v15
	v_lshlrev_b32_e32 v143, 4, v3
	v_bitop3_b32 v3, v12, v13, 8 bitop3:0x36
	v_lshlrev_b32_e32 v130, 13, v0
	v_lshlrev_b32_e32 v145, 4, v3
	v_bitop3_b32 v3, v12, v13, 10 bitop3:0x36
	v_lshl_or_b32 v102, v0, 5, v18
	v_max_i32_e32 v0, 0x300, v66
	v_lshlrev_b32_e32 v147, 4, v3
	v_bitop3_b32 v3, v12, v13, 12 bitop3:0x36
	v_sub_u32_e32 v0, v0, v66
	v_lshlrev_b32_e32 v149, 4, v3
	v_bitop3_b32 v3, v12, v13, 14 bitop3:0x36
	v_add_u32_e32 v0, 0x1ff, v0
	v_lshlrev_b32_e32 v20, 5, v31
	v_lshlrev_b32_e32 v151, 4, v3
	v_lshrrev_b32_e32 v3, 9, v0
	v_and_b32_e32 v16, -2, v15
	v_lshlrev_b32_e32 v4, 3, v31
	v_lshl_or_b32 v6, v31, 3, 32
	v_lshl_or_b32 v8, v31, 3, 64
	s_waitcnt lgkmcnt(0)
	v_lshlrev_b32_e32 v10, 3, v31
	v_or_b32_e32 v10, 0x60, v10
	v_add_u32_e32 v119, s1, v20
	v_add_u32_e32 v120, s72, v20
	v_bitop3_b32 v20, v31, v68, 15 bitop3:0x78
	v_add_u32_e32 v3, 1, v3
	v_readlane_b32 s54, v253, 48
	v_readlane_b32 s55, v253, 49
	v_lshl_add_u32 v14, v68, 8, 0
	v_ashrrev_i32_e32 v5, 31, v4
	v_ashrrev_i32_e32 v7, 31, v6
	v_ashrrev_i32_e32 v9, 31, v8
	v_ashrrev_i32_e32 v11, 31, v10
	v_lshlrev_b32_e32 v20, 4, v20
	v_lshl_or_b32 v84, v31, 10, v68
	v_lshlrev_b32_e32 v22, 4, v22
	v_lshlrev_b32_e32 v21, 4, v21
	v_lshlrev_b32_e32 v19, 4, v19
	v_lshlrev_b32_e32 v23, 8, v76
	v_lshlrev_b32_e32 v92, 7, v76
	v_lshlrev_b32_e32 v25, 8, v78
	v_lshlrev_b32_e32 v94, 7, v78
	v_lshlrev_b32_e32 v27, 8, v80
	v_lshlrev_b32_e32 v96, 7, v80
	v_lshlrev_b32_e32 v29, 8, v82
	v_lshlrev_b32_e32 v98, 7, v82
	v_lshl_or_b32 v100, v16, 5, v18
	s_movk_i32 s0, 0x1ff
	v_and_b32_e32 v153, 0xfffffe, v3
	v_ashrrev_i32_e32 v85, 31, v84
	v_ashrrev_i32_e32 v77, 31, v76
	v_ashrrev_i32_e32 v87, 31, v86
	v_ashrrev_i32_e32 v79, 31, v78
	v_ashrrev_i32_e32 v89, 31, v88
	v_ashrrev_i32_e32 v81, 31, v80
	v_ashrrev_i32_e32 v91, 31, v90
	v_ashrrev_i32_e32 v83, 31, v82
	v_ashrrev_i32_e32 v93, 31, v92
	v_ashrrev_i32_e32 v95, 31, v94
	v_ashrrev_i32_e32 v97, 31, v96
	v_ashrrev_i32_e32 v99, 31, v98
	v_lshlrev_b32_e32 v127, 13, v16
	v_add_u32_e32 v129, v17, v128
	v_add_u32_e32 v132, v17, v131
	v_add_u32_e32 v142, v17, v133
	v_add_u32_e32 v144, v17, v143
	v_add_u32_e32 v146, v17, v145
	v_add_u32_e32 v148, v17, v147
	v_add_u32_e32 v150, v17, v149
	v_add_u32_e32 v152, v17, v151
	v_ashrrev_i32_e32 v101, 31, v100
	v_ashrrev_i32_e32 v103, 31, v102
	v_cmp_lt_u32_e64 s[54:55], s0, v0
	v_lshl_add_u32 v154, v153, 9, v66
	s_mov_b32 s73, s28
	s_mov_b32 s74, s37
	s_mov_b32 s75, s70
	s_mov_b32 s76, s71
	v_cmp_ne_u32_e64 s[56:57], v3, v153
	v_lshl_add_u32 v155, v66, 2, s1
	v_lshlrev_b64 v[104:105], 1, v[4:5]
	v_lshlrev_b64 v[106:107], 1, v[6:7]
	v_lshlrev_b64 v[108:109], 1, v[8:9]
	v_lshlrev_b64 v[110:111], 1, v[10:11]
	v_add_u32_e32 v156, v14, v20
	v_lshlrev_b32_e32 v0, 1, v2
	v_add_u32_e32 v157, v14, v22
	v_add_u32_e32 v158, v14, v21
	v_add_u32_e32 v159, v14, v19
	v_add_u32_e32 v160, v24, v23
	v_add_u32_e32 v161, v26, v25
	v_add_u32_e32 v162, v28, v27
	v_add_u32_e32 v163, v30, v29
	s_mov_b32 s40, s2
	s_branch .LBB0_1127
